# lrprep loop: first load no longer waited with vmcnt(0) before the other three loads are issued (wait moved behind them, vmcnt(3))
# baseline (speedup 1.0000x reference)
; DI int bidx() { int t = blockIdx.x; asm volatile("" : "+s"(t)); return t; }
; DI float lo_bf(unsigned u) { return __uint_as_float(u << 16); }
; DI float hi_bf(unsigned u) { return __uint_as_float(u & 0xFFFF0000u); }
; DI void phase_lrprep(PP p, int l) {
;     ...
;     for (int r0 = ((int)bidx() * 512 + tid) >> 5; r0 < MT; r0 += 2 * rstep) {
;         u32x4 cu[2], pu[2]; bool first[2], valid[2];
; #pragma unroll
;         for (int k = 0; k < 2; ++k) {
;             const int r = r0 + k * rstep; valid[k] = r < MT; const int rr = valid[k] ? r : r0;
;             first[k] = rr < MP ? ((rr & 2047) == 0) : (((rr - MP) & 31) == 0);
;             cu[k] = *(const u32x4*)(zs + (size_t)rr * ZS_LD + 1536 + c8);
;             pu[k] = *(const u32x4*)(zs + (size_t)(first[k] ? rr : rr - 1) * ZS_LD + 1536 + c8);
;         }
; #pragma unroll
;         for (int k = 0; k < 2; ++k) {
;             const int r = r0 + k * rstep;
;             if (!valid[k]) continue;
;             float x[8], pv[8];
; #pragma unroll
;             for (int j = 0; j < 4; ++j) { x[2 * j] = lo_bf(cu[k][j]); x[2 * j + 1] = hi_bf(cu[k][j]); pv[2 * j] = lo_bf(pu[k][j]); pv[2 * j + 1] = hi_bf(pu[k][j]); }
;             if (first[k]) {
;                 if (r >= MP) { const float* s = sh0 + (size_t)((r - MP) >> 5) * 1792 + c8;
; #pragma unroll
;                     for (int j = 0; j < 8; ++j) pv[j] = s[j]; }
.LBB0_121:
	v_add_u32_e32 v36, s69, v38
	s_mov_b32 s6, 0x8400
	v_cmp_gt_i32_e32 vcc, s6, v36
	s_movk_i32 s8, 0xe00
	v_ashrrev_i32_e32 v39, 31, v38
	v_cndmask_b32_e32 v0, v38, v36, vcc
	v_cmp_gt_i32_e64 s[6:7], s95, v0
	s_nop 1
	v_cndmask_b32_e64 v10, 31, v219, s[6:7]
	v_and_b32_e32 v22, v10, v0
	v_mad_i64_i32 v[10:11], s[6:7], v0, s8, v[34:35]
	v_cmp_gt_i32_e64 s[6:7], s95, v38
	s_nop 1
	v_cndmask_b32_e64 v12, 31, v219, s[6:7]
	v_and_b32_e32 v23, v12, v38
	v_cmp_ne_u32_e64 s[6:7], 0, v23
	s_nop 1
	v_subbrev_co_u32_e64 v12, s[6:7], 0, v38, s[6:7]
	v_mad_i64_i32 v[12:13], s[6:7], v12, s8, v[34:35]
	v_cmp_ne_u32_e64 s[6:7], 0, v22
	global_load_dwordx4 v[18:21], v[12:13], off offset:3072
	s_nop 1
	v_subbrev_co_u32_e64 v0, s[6:7], 0, v0, s[6:7]
	v_mad_i64_i32 v[14:15], s[6:7], v0, s8, v[34:35]
	v_mad_i64_i32 v[12:13], s[6:7], v38, s8, v[34:35]
	global_load_dwordx4 v[26:29], v[12:13], off offset:3072
	s_nop 0
	global_load_dwordx4 v[10:13], v[10:11], off offset:3072
	s_nop 0
	global_load_dwordx4 v[14:17], v[14:15], off offset:3072
	s_waitcnt vmcnt(3)
	v_lshlrev_b32_e32 v24, 16, v19
	v_cmp_eq_u32_e64 s[8:9], 0, v23
	v_cmp_eq_u32_e64 s[6:7], 0, v22
	v_lshlrev_b32_e32 v22, 16, v18
	v_and_b32_e32 v23, 0xffff0000, v18
	v_and_b32_e32 v25, 0xffff0000, v19
	v_lshlrev_b32_e32 v18, 16, v20
	v_and_b32_e32 v19, 0xffff0000, v20
	v_lshlrev_b32_e32 v20, 16, v21
	v_and_b32_e32 v21, 0xffff0000, v21
	s_and_saveexec_b64 s[22:23], s[8:9]
	s_cbranch_execz .LBB0_125
	v_cmp_lt_i32_e64 s[8:9], s96, v38
	v_mov_b32_e32 v21, 0
	v_mov_b32_e32 v20, 0
	v_mov_b32_e32 v19, 0
	v_mov_b32_e32 v18, 0
	v_mov_b32_e32 v25, 0
	v_mov_b32_e32 v24, 0
	v_mov_b32_e32 v23, 0
	v_mov_b32_e32 v22, 0
	s_and_saveexec_b64 s[28:29], s[8:9]
	s_cbranch_execz .LBB0_124
	v_add_u32_e32 v0, 0xffff8000, v38
	v_lshrrev_b32_e32 v0, 5, v0
	s_movk_i32 s8, 0x1c00
	v_mad_u64_u32 v[18:19], s[8:9], v0, s8, v[30:31]
	global_load_dwordx4 v[22:25], v[18:19], off
	s_nop 0
	global_load_dwordx4 v[18:21], v[18:19], off offset:16
